# phase5 out-proj epilogue: x residual loads batched 16-wide double-buffered instead of one load-wait-add-store per element (plus clean peeled last k-step)
# speedup vs baseline: 1.0815x; 1.0403x over previous
; #define MFMA32(a, b, c) __builtin_amdgcn_mfma_f32_32x32x16_bf16((a), (b), (c), 0, 0, 0)
; template <class Epi>
; DI void gemm256(const bf16_t* __restrict__ A, int lda, const bf16_t* __restrict__ B, int ldb, int K, int m0, int n0,
;                 bf16_t* sA, bf16_t* sB, Epi epi) {
;     ...
;   for (int kt = 0; kt < nk; ++kt) {
;     __syncthreads();
;     *(u32x4*)(sA + (lr) * LDS_ROW + lc) = ra0; *(u32x4*)(sA + (lr + 32) * LDS_ROW + lc) = ra1;
;     *(u32x4*)(sA + (lr + 64) * LDS_ROW + lc) = ra2; *(u32x4*)(sA + (lr + 96) * LDS_ROW + lc) = ra3;
;     *(u32x4*)(sA + (lr + 128) * LDS_ROW + lc) = ra4; *(u32x4*)(sA + (lr + 160) * LDS_ROW + lc) = ra5;
;     *(u32x4*)(sA + (lr + 192) * LDS_ROW + lc) = ra6; *(u32x4*)(sA + (lr + 224) * LDS_ROW + lc) = ra7;
;     *(u32x4*)(sB + (lr) * LDS_ROW + lc) = rb0; *(u32x4*)(sB + (lr + 32) * LDS_ROW + lc) = rb1;
;     *(u32x4*)(sB + (lr + 64) * LDS_ROW + lc) = rb2; *(u32x4*)(sB + (lr + 96) * LDS_ROW + lc) = rb3;
;     __syncthreads();
;     if (kt + 1 < nk) {
;       const int ko2 = (kt + 1) * 64;
;       G256_LOAD(ko2)
;     }
; #pragma unroll
;     for (int s = 0; s < 4; ++s) {
;       const int ko = s * 16 + (lane >> 5) * 8;
;       bf16x8 b0 = *(const bf16x8*)(sB + (wn * 64 + (lane & 31)) * LDS_ROW + ko);
;       bf16x8 b1 = *(const bf16x8*)(sB + (wn * 64 + 32 + (lane & 31)) * LDS_ROW + ko);
; #pragma unroll
;       for (int i = 0; i < 4; ++i) {
;         bf16x8 a = *(const bf16x8*)(sA + (wm * 128 + i * 32 + (lane & 31)) * LDS_ROW + ko);
;         acc[i][0] = MFMA32(a, b0, acc[i][0]);
;         acc[i][1] = MFMA32(a, b1, acc[i][1]);
;       }
;     }
.LBB0_921:
	s_barrier
	s_waitcnt vmcnt(5)
	ds_write_b128 v178, v[156:159]
	ds_write_b128 v178, v[128:131] offset:4608
	ds_write_b128 v178, v[132:135] offset:9216
	ds_write_b128 v178, v[136:139] offset:13824
	ds_write_b128 v178, v[140:143] offset:18432
	ds_write_b128 v178, v[144:147] offset:23040
	ds_write_b128 v178, v[148:151] offset:27648
	s_waitcnt vmcnt(3)
	ds_write_b128 v178, v[160:163] offset:32256
	ds_write_b128 v178, v[152:155] offset:36864
	s_waitcnt vmcnt(2)
	ds_write_b128 v178, v[164:167] offset:41472
	s_waitcnt vmcnt(1)
	ds_write_b128 v178, v[168:171] offset:46080
	s_waitcnt vmcnt(0)
	ds_write_b128 v178, v[172:175] offset:50688
	s_waitcnt lgkmcnt(0)
	s_barrier
	ds_read_b128 v[128:131], v179
	ds_read_b128 v[132:135], v184 offset:36864
	ds_read_b128 v[136:139], v184 offset:36896
	ds_read_b128 v[140:143], v179 offset:32
	ds_read_b128 v[144:147], v184 offset:41472
	ds_read_b128 v[148:151], v184 offset:41504
	s_waitcnt lgkmcnt(4)
	v_mfma_f32_32x32x16_bf16 v[112:127], v[128:131], v[132:135], v[112:127]
	s_waitcnt lgkmcnt(1)
	v_mfma_f32_32x32x16_bf16 v[96:111], v[128:131], v[144:147], v[96:111]
	ds_read_b128 v[128:131], v179 offset:4608
	ds_read_b128 v[152:155], v179 offset:4640
	s_waitcnt lgkmcnt(1)
	v_mfma_f32_32x32x16_bf16 v[80:95], v[128:131], v[132:135], v[80:95]
	v_mfma_f32_32x32x16_bf16 v[64:79], v[128:131], v[144:147], v[64:79]
	ds_read_b128 v[128:131], v179 offset:9216
	ds_read_b128 v[156:159], v179 offset:9248
	s_waitcnt lgkmcnt(1)
	v_mfma_f32_32x32x16_bf16 v[48:63], v[128:131], v[132:135], v[48:63]
	v_mfma_f32_32x32x16_bf16 v[32:47], v[128:131], v[144:147], v[32:47]
	ds_read_b128 v[128:131], v176
	ds_read_b128 v[160:163], v176 offset:32
	s_waitcnt lgkmcnt(1)
	v_mfma_f32_32x32x16_bf16 v[16:31], v[128:131], v[132:135], v[16:31]
	v_mfma_f32_32x32x16_bf16 v[112:127], v[140:143], v[136:139], v[112:127]
	v_mfma_f32_32x32x16_bf16 v[96:111], v[140:143], v[148:151], v[96:111]
	v_mfma_f32_32x32x16_bf16 v[0:15], v[128:131], v[144:147], v[0:15]
	v_mfma_f32_32x32x16_bf16 v[80:95], v[152:155], v[136:139], v[80:95]
	v_mfma_f32_32x32x16_bf16 v[64:79], v[152:155], v[148:151], v[64:79]
	v_mfma_f32_32x32x16_bf16 v[48:63], v[156:159], v[136:139], v[48:63]
	s_waitcnt lgkmcnt(0)
	v_mfma_f32_32x32x16_bf16 v[16:31], v[160:163], v[136:139], v[16:31]
	ds_read_b128 v[128:131], v179 offset:64
	ds_read_b128 v[132:135], v184 offset:36928
	ds_read_b128 v[172:175], v184 offset:36960
	ds_read_b128 v[136:139], v179 offset:96
	ds_read_b128 v[140:143], v184 offset:41536
	ds_read_b128 v[188:191], v184 offset:41568
	v_mfma_f32_32x32x16_bf16 v[32:47], v[156:159], v[148:151], v[32:47]
	s_waitcnt lgkmcnt(4)
	v_mfma_f32_32x32x16_bf16 v[112:127], v[128:131], v[132:135], v[112:127]
	s_waitcnt lgkmcnt(1)
	v_mfma_f32_32x32x16_bf16 v[96:111], v[128:131], v[140:143], v[96:111]
	ds_read_b128 v[128:131], v179 offset:4672
	ds_read_b128 v[144:147], v179 offset:4704
	v_mfma_f32_32x32x16_bf16 v[0:15], v[160:163], v[148:151], v[0:15]
	s_waitcnt lgkmcnt(1)
	v_mfma_f32_32x32x16_bf16 v[80:95], v[128:131], v[132:135], v[80:95]
	v_mfma_f32_32x32x16_bf16 v[64:79], v[128:131], v[140:143], v[64:79]
	ds_read_b128 v[128:131], v179 offset:9280
	ds_read_b128 v[148:151], v179 offset:9312
	s_waitcnt lgkmcnt(1)
	v_mfma_f32_32x32x16_bf16 v[48:63], v[128:131], v[132:135], v[48:63]
	v_mfma_f32_32x32x16_bf16 v[32:47], v[128:131], v[140:143], v[32:47]
	ds_read_b128 v[128:131], v176 offset:64
	ds_read_b128 v[194:197], v176 offset:96
	s_waitcnt lgkmcnt(1)
	v_mfma_f32_32x32x16_bf16 v[16:31], v[128:131], v[132:135], v[16:31]
	v_lshl_add_u64 v[132:133], v[180:181], 0, s[10:11]
	v_add_co_u32_e32 v152, vcc, s21, v132
	v_lshl_add_u64 v[134:135], v[182:183], 0, s[10:11]
	s_nop 0
	v_addc_co_u32_e32 v153, vcc, 0, v133, vcc
	s_add_u32 s10, s10, 0x80
	v_mfma_f32_32x32x16_bf16 v[0:15], v[128:131], v[140:143], v[0:15]
	v_add_co_u32_e32 v128, vcc, s26, v132
	s_addc_u32 s11, s11, 0
	s_nop 0
	v_addc_co_u32_e32 v129, vcc, 0, v133, vcc
	v_add_co_u32_e32 v140, vcc, s27, v132
	v_mfma_f32_32x32x16_bf16 v[112:127], v[136:139], v[172:175], v[112:127]
	s_nop 0
	v_addc_co_u32_e32 v141, vcc, 0, v133, vcc
	v_add_co_u32_e32 v142, vcc, s28, v132
	s_cmpk_lg_i32 s10, 0x780
	s_nop 0
	v_addc_co_u32_e32 v143, vcc, 0, v133, vcc
	v_add_co_u32_e32 v154, vcc, s29, v132
	v_mfma_f32_32x32x16_bf16 v[96:111], v[136:139], v[188:191], v[96:111]
	s_nop 0
	v_addc_co_u32_e32 v155, vcc, 0, v133, vcc
	v_add_co_u32_e32 v160, vcc, s30, v132
	s_nop 1
	v_addc_co_u32_e32 v161, vcc, 0, v133, vcc
	v_add_co_u32_e32 v162, vcc, s31, v132
	v_mfma_f32_32x32x16_bf16 v[80:95], v[144:147], v[172:175], v[80:95]
	s_nop 0
	v_addc_co_u32_e32 v163, vcc, 0, v133, vcc
	v_add_co_u32_e32 v164, vcc, s34, v132
	s_nop 1
	v_addc_co_u32_e32 v165, vcc, 0, v133, vcc
	v_add_co_u32_e32 v166, vcc, s35, v134
	v_mfma_f32_32x32x16_bf16 v[64:79], v[144:147], v[188:191], v[64:79]
	s_nop 0
	v_addc_co_u32_e32 v167, vcc, 0, v135, vcc
	v_add_co_u32_e32 v168, vcc, s36, v134
	s_nop 1
	v_addc_co_u32_e32 v169, vcc, 0, v135, vcc
	v_add_co_u32_e32 v170, vcc, s37, v134
	v_mfma_f32_32x32x16_bf16 v[48:63], v[148:151], v[172:175], v[48:63]
	s_nop 0
	v_addc_co_u32_e32 v171, vcc, 0, v135, vcc
	v_add_co_u32_e32 v198, vcc, s42, v134
	s_nop 1
	v_addc_co_u32_e32 v199, vcc, 0, v135, vcc
	global_load_dwordx4 v[156:159], v[152:153], off offset:128
	s_nop 0
	global_load_dwordx4 v[128:131], v[128:129], off offset:128
	s_nop 0
	global_load_dwordx4 v[132:135], v[140:141], off offset:128
	global_load_dwordx4 v[136:139], v[142:143], off offset:128
	v_mfma_f32_32x32x16_bf16 v[32:47], v[148:151], v[188:191], v[32:47]
	global_load_dwordx4 v[140:143], v[154:155], off offset:128
	global_load_dwordx4 v[144:147], v[160:161], off offset:128
	global_load_dwordx4 v[148:151], v[162:163], off offset:128
	s_nop 0
	global_load_dwordx4 v[160:163], v[164:165], off offset:128
	global_load_dwordx4 v[152:155], v[166:167], off offset:128
	s_nop 0
	global_load_dwordx4 v[164:167], v[168:169], off offset:128
	s_nop 0
	global_load_dwordx4 v[168:171], v[170:171], off offset:128
	s_waitcnt lgkmcnt(0)
	v_mfma_f32_32x32x16_bf16 v[16:31], v[194:197], v[172:175], v[16:31]
	global_load_dwordx4 v[172:175], v[198:199], off offset:128
	v_mfma_f32_32x32x16_bf16 v[0:15], v[194:197], v[188:191], v[0:15]
	s_cbranch_scc1 .LBB0_921
; #define MFMA32(a, b, c) __builtin_amdgcn_mfma_f32_32x32x16_bf16((a), (b), (c), 0, 0, 0)
; DI int crow32(int r, int half) { return (r & 3) + 8 * (r >> 2) + 4 * half; }
; template <class Epi>
; DI void gemm256(const bf16_t* __restrict__ A, int lda, const bf16_t* __restrict__ B, int ldb, int K, int m0, int n0,
;                 bf16_t* sA, bf16_t* sB, Epi epi) {
;     ...
;   for (int kt = 0; kt < nk; ++kt) {
;     __syncthreads();
;     *(u32x4*)(sA + (lr) * LDS_ROW + lc) = ra0; *(u32x4*)(sA + (lr + 32) * LDS_ROW + lc) = ra1;
;     *(u32x4*)(sA + (lr + 64) * LDS_ROW + lc) = ra2; *(u32x4*)(sA + (lr + 96) * LDS_ROW + lc) = ra3;
;     *(u32x4*)(sA + (lr + 128) * LDS_ROW + lc) = ra4; *(u32x4*)(sA + (lr + 160) * LDS_ROW + lc) = ra5;
;     *(u32x4*)(sA + (lr + 192) * LDS_ROW + lc) = ra6; *(u32x4*)(sA + (lr + 224) * LDS_ROW + lc) = ra7;
;     *(u32x4*)(sB + (lr) * LDS_ROW + lc) = rb0; *(u32x4*)(sB + (lr + 32) * LDS_ROW + lc) = rb1;
;     *(u32x4*)(sB + (lr + 64) * LDS_ROW + lc) = rb2; *(u32x4*)(sB + (lr + 96) * LDS_ROW + lc) = rb3;
;     __syncthreads();
;     if (kt + 1 < nk) {
;       const int ko2 = (kt + 1) * 64;
;       G256_LOAD(ko2)
;     }
; #pragma unroll
;     for (int s = 0; s < 4; ++s) {
;       const int ko = s * 16 + (lane >> 5) * 8;
;       bf16x8 b0 = *(const bf16x8*)(sB + (wn * 64 + (lane & 31)) * LDS_ROW + ko);
;       bf16x8 b1 = *(const bf16x8*)(sB + (wn * 64 + 32 + (lane & 31)) * LDS_ROW + ko);
; #pragma unroll
;       for (int i = 0; i < 4; ++i) {
;         bf16x8 a = *(const bf16x8*)(sA + (wm * 128 + i * 32 + (lane & 31)) * LDS_ROW + ko);
;         acc[i][0] = MFMA32(a, b0, acc[i][0]);
;         acc[i][1] = MFMA32(a, b1, acc[i][1]);
;       }
;     }
;     ...
; #pragma unroll
;   for (int i = 0; i < 4; ++i)
; #pragma unroll
;     for (int j = 0; j < 2; ++j)
; #pragma unroll
;       for (int r = 0; r < 16; ++r) {
;         const int m = m0 + wm * 128 + i * 32 + crow32(r, lane >> 5);
;         const int n = n0 + wn * 64 + j * 32 + (lane & 31);
;         epi(m, n, acc[i][j][r]);
;       }
	s_barrier
	s_waitcnt vmcnt(11)
	ds_write_b128 v178, v[156:159]
	s_waitcnt vmcnt(10)
	ds_write_b128 v178, v[128:131] offset:4608
	s_waitcnt vmcnt(9)
	ds_write_b128 v178, v[132:135] offset:9216
	s_waitcnt vmcnt(8)
	ds_write_b128 v178, v[136:139] offset:13824
	s_waitcnt vmcnt(7)
	ds_write_b128 v178, v[140:143] offset:18432
	s_waitcnt vmcnt(6)
	ds_write_b128 v178, v[144:147] offset:23040
	s_waitcnt vmcnt(5)
	ds_write_b128 v178, v[148:151] offset:27648
	s_waitcnt vmcnt(4)
	ds_write_b128 v178, v[160:163] offset:32256
	s_waitcnt vmcnt(3)
	ds_write_b128 v178, v[152:155] offset:36864
	s_waitcnt vmcnt(2)
	ds_write_b128 v178, v[164:167] offset:41472
	s_waitcnt vmcnt(1)
	ds_write_b128 v178, v[168:171] offset:46080
	s_waitcnt vmcnt(0)
	ds_write_b128 v178, v[172:175] offset:50688
	s_waitcnt lgkmcnt(0)
	s_barrier
	ds_read_b128 v[128:131], v179
	ds_read_b128 v[132:135], v184 offset:36864
	ds_read_b128 v[136:139], v184 offset:36896
	ds_read_b128 v[140:143], v179 offset:32
	ds_read_b128 v[144:147], v184 offset:41472
	ds_read_b128 v[148:151], v184 offset:41504
	s_waitcnt lgkmcnt(4)
	v_mfma_f32_32x32x16_bf16 v[112:127], v[128:131], v[132:135], v[112:127]
	s_waitcnt lgkmcnt(1)
	v_mfma_f32_32x32x16_bf16 v[96:111], v[128:131], v[144:147], v[96:111]
	ds_read_b128 v[128:131], v179 offset:4608
	ds_read_b128 v[152:155], v179 offset:4640
	s_waitcnt lgkmcnt(1)
	v_mfma_f32_32x32x16_bf16 v[80:95], v[128:131], v[132:135], v[80:95]
	v_mfma_f32_32x32x16_bf16 v[64:79], v[128:131], v[144:147], v[64:79]
	ds_read_b128 v[128:131], v179 offset:9216
	ds_read_b128 v[156:159], v179 offset:9248
	s_waitcnt lgkmcnt(1)
	v_mfma_f32_32x32x16_bf16 v[48:63], v[128:131], v[132:135], v[48:63]
	v_mfma_f32_32x32x16_bf16 v[32:47], v[128:131], v[144:147], v[32:47]
	ds_read_b128 v[128:131], v176
	ds_read_b128 v[160:163], v176 offset:32
	s_waitcnt lgkmcnt(1)
	v_mfma_f32_32x32x16_bf16 v[16:31], v[128:131], v[132:135], v[16:31]
	v_mfma_f32_32x32x16_bf16 v[112:127], v[140:143], v[136:139], v[112:127]
	v_mfma_f32_32x32x16_bf16 v[96:111], v[140:143], v[148:151], v[96:111]
	v_mfma_f32_32x32x16_bf16 v[0:15], v[128:131], v[144:147], v[0:15]
	v_mfma_f32_32x32x16_bf16 v[80:95], v[152:155], v[136:139], v[80:95]
	v_mfma_f32_32x32x16_bf16 v[64:79], v[152:155], v[148:151], v[64:79]
	v_mfma_f32_32x32x16_bf16 v[48:63], v[156:159], v[136:139], v[48:63]
	s_waitcnt lgkmcnt(0)
	v_mfma_f32_32x32x16_bf16 v[16:31], v[160:163], v[136:139], v[16:31]
	ds_read_b128 v[128:131], v179 offset:64
	ds_read_b128 v[132:135], v184 offset:36928
	ds_read_b128 v[172:175], v184 offset:36960
	ds_read_b128 v[136:139], v179 offset:96
	ds_read_b128 v[140:143], v184 offset:41536
	ds_read_b128 v[188:191], v184 offset:41568
	v_mfma_f32_32x32x16_bf16 v[32:47], v[156:159], v[148:151], v[32:47]
	s_waitcnt lgkmcnt(4)
	v_mfma_f32_32x32x16_bf16 v[112:127], v[128:131], v[132:135], v[112:127]
	s_waitcnt lgkmcnt(1)
	v_mfma_f32_32x32x16_bf16 v[96:111], v[128:131], v[140:143], v[96:111]
	ds_read_b128 v[128:131], v179 offset:4672
	ds_read_b128 v[144:147], v179 offset:4704
	v_mfma_f32_32x32x16_bf16 v[0:15], v[160:163], v[148:151], v[0:15]
	s_waitcnt lgkmcnt(1)
	v_mfma_f32_32x32x16_bf16 v[80:95], v[128:131], v[132:135], v[80:95]
	v_mfma_f32_32x32x16_bf16 v[64:79], v[128:131], v[140:143], v[64:79]
	ds_read_b128 v[128:131], v179 offset:9280
	ds_read_b128 v[148:151], v179 offset:9312
	s_waitcnt lgkmcnt(1)
	v_mfma_f32_32x32x16_bf16 v[48:63], v[128:131], v[132:135], v[48:63]
	v_mfma_f32_32x32x16_bf16 v[32:47], v[128:131], v[140:143], v[32:47]
	ds_read_b128 v[128:131], v176 offset:64
	ds_read_b128 v[194:197], v176 offset:96
	s_waitcnt lgkmcnt(1)
	v_mfma_f32_32x32x16_bf16 v[16:31], v[128:131], v[132:135], v[16:31]
	v_mfma_f32_32x32x16_bf16 v[0:15], v[128:131], v[140:143], v[0:15]
	v_mfma_f32_32x32x16_bf16 v[112:127], v[136:139], v[172:175], v[112:127]
	v_mfma_f32_32x32x16_bf16 v[96:111], v[136:139], v[188:191], v[96:111]
	v_mfma_f32_32x32x16_bf16 v[80:95], v[144:147], v[172:175], v[80:95]
	v_mfma_f32_32x32x16_bf16 v[64:79], v[144:147], v[188:191], v[64:79]
	v_mfma_f32_32x32x16_bf16 v[48:63], v[148:151], v[172:175], v[48:63]
	v_mfma_f32_32x32x16_bf16 v[32:47], v[148:151], v[188:191], v[32:47]
	s_waitcnt lgkmcnt(0)
	v_mfma_f32_32x32x16_bf16 v[16:31], v[194:197], v[172:175], v[16:31]
	v_mfma_f32_32x32x16_bf16 v[0:15], v[194:197], v[188:191], v[0:15]
	v_and_b32_e32 v200, 0xffffff80, v185
	v_lshrrev_b32_e32 v201, 3, v185
	v_add_u32_e32 v200, s44, v200
	v_and_or_b32 v200, v201, 4, v200
	v_or_b32_e32 v201, s45, v186
	v_lshlrev_b32_e32 v200, 12, v200
	v_lshl_add_u32 v200, v201, 2, v200
	v_mov_b32_e32 v202, v200
	v_add_u32_e32 v203, 0x1000, v200
	v_add_u32_e32 v204, 0x2000, v200
	v_add_u32_e32 v205, 0x3000, v200
	v_add_u32_e32 v206, 0x8000, v200
	v_add_u32_e32 v207, 0x9000, v200
	v_add_u32_e32 v208, 0xa000, v200
	v_add_u32_e32 v209, 0xb000, v200
	v_add_u32_e32 v210, 0x10000, v200
	v_add_u32_e32 v211, 0x11000, v200
	v_add_u32_e32 v212, 0x12000, v200
	v_add_u32_e32 v213, 0x13000, v200
	v_add_u32_e32 v214, 0x18000, v200
	v_add_u32_e32 v215, 0x19000, v200
	v_add_u32_e32 v216, 0x1a000, v200
	v_add_u32_e32 v217, 0x1b000, v200
	v_mov_b32_e32 v128, v202
	global_load_dword v144, v128, s[68:69]
	v_mov_b32_e32 v129, v203
	global_load_dword v145, v129, s[68:69]
	v_mov_b32_e32 v130, v204
	global_load_dword v146, v130, s[68:69]
	v_mov_b32_e32 v131, v205
	global_load_dword v147, v131, s[68:69]
	v_mov_b32_e32 v132, v206
	global_load_dword v148, v132, s[68:69]
	v_mov_b32_e32 v133, v207
	global_load_dword v149, v133, s[68:69]
	v_mov_b32_e32 v134, v208
	global_load_dword v150, v134, s[68:69]
	v_mov_b32_e32 v135, v209
	global_load_dword v151, v135, s[68:69]
	v_mov_b32_e32 v136, v210
; DI int crow32(int r, int half) { return (r & 3) + 8 * (r >> 2) + 4 * half; }
; template <class Epi>
; DI void gemm256(const bf16_t* __restrict__ A, int lda, const bf16_t* __restrict__ B, int ldb, int K, int m0, int n0,
;                 bf16_t* sA, bf16_t* sB, Epi epi) {
;     ...
; #pragma unroll
;   for (int i = 0; i < 4; ++i)
; #pragma unroll
;     for (int j = 0; j < 2; ++j)
; #pragma unroll
;       for (int r = 0; r < 16; ++r) {
;         const int m = m0 + wm * 128 + i * 32 + crow32(r, lane >> 5);
;         const int n = n0 + wn * 64 + j * 32 + (lane & 31);
;         epi(m, n, acc[i][j][r]);
;       }
; __global__ void __launch_bounds__(256, 2) hymba_mega(Params p) {
;     ...
;       const int mt = (tile & 7) * 8 + (tile >> 6), nt = (tile >> 3) & 7;
;       gemm256((const bf16_t*)(ws + OFF_MX), 1024, (const bf16_t*)(ws + OFF_WOUTT), 1024, 1024, mt * 256, nt * 128, sA, (bf16_t*)(smem + 36864),
;               [&](int m, int n, float v) { out[(size_t)m * 1024 + n] = x[(size_t)m * 1024 + n] + v; });
	global_load_dword v152, v136, s[68:69]
	v_mov_b32_e32 v137, v211
	global_load_dword v153, v137, s[68:69]
	v_mov_b32_e32 v138, v212
	global_load_dword v154, v138, s[68:69]
	v_mov_b32_e32 v139, v213
	global_load_dword v155, v139, s[68:69]
	v_mov_b32_e32 v140, v214
	global_load_dword v156, v140, s[68:69]
	v_mov_b32_e32 v141, v215
	global_load_dword v157, v141, s[68:69]
	v_mov_b32_e32 v142, v216
	global_load_dword v158, v142, s[68:69]
	v_mov_b32_e32 v143, v217
	global_load_dword v159, v143, s[68:69]
	v_add_u32_e32 v160, 0x80, v202
	global_load_dword v236, v160, s[68:69]
	v_add_u32_e32 v161, 0x80, v203
	global_load_dword v237, v161, s[68:69]
	v_add_u32_e32 v162, 0x80, v204
	global_load_dword v238, v162, s[68:69]
	v_add_u32_e32 v163, 0x80, v205
	global_load_dword v239, v163, s[68:69]
	v_add_u32_e32 v164, 0x80, v206
	global_load_dword v240, v164, s[68:69]
	v_add_u32_e32 v165, 0x80, v207
	global_load_dword v241, v165, s[68:69]
	v_add_u32_e32 v166, 0x80, v208
	global_load_dword v242, v166, s[68:69]
	v_add_u32_e32 v167, 0x80, v209
	global_load_dword v243, v167, s[68:69]
	v_add_u32_e32 v168, 0x80, v210
	global_load_dword v244, v168, s[68:69]
	v_add_u32_e32 v169, 0x80, v211
	global_load_dword v245, v169, s[68:69]
	v_add_u32_e32 v170, 0x80, v212
	global_load_dword v246, v170, s[68:69]
	v_add_u32_e32 v171, 0x80, v213
	global_load_dword v247, v171, s[68:69]
	v_add_u32_e32 v172, 0x80, v214
	global_load_dword v248, v172, s[68:69]
	v_add_u32_e32 v173, 0x80, v215
	global_load_dword v249, v173, s[68:69]
	v_add_u32_e32 v174, 0x80, v216
	global_load_dword v250, v174, s[68:69]
	v_add_u32_e32 v175, 0x80, v217
	global_load_dword v251, v175, s[68:69]
	s_waitcnt vmcnt(16)
	v_add_f32_e32 v144, v112, v144
	global_store_dword v128, v144, s[84:85]
	v_add_f32_e32 v145, v113, v145
	global_store_dword v129, v145, s[84:85]
	v_add_f32_e32 v146, v114, v146
	global_store_dword v130, v146, s[84:85]
	v_add_f32_e32 v147, v115, v147
	global_store_dword v131, v147, s[84:85]
	v_add_f32_e32 v148, v116, v148
	global_store_dword v132, v148, s[84:85]
	v_add_f32_e32 v149, v117, v149
	global_store_dword v133, v149, s[84:85]
	v_add_f32_e32 v150, v118, v150
	global_store_dword v134, v150, s[84:85]
	v_add_f32_e32 v151, v119, v151
	global_store_dword v135, v151, s[84:85]
	v_add_f32_e32 v152, v120, v152
	global_store_dword v136, v152, s[84:85]
	v_add_f32_e32 v153, v121, v153
	global_store_dword v137, v153, s[84:85]
	v_add_f32_e32 v154, v122, v154
	global_store_dword v138, v154, s[84:85]
	v_add_f32_e32 v155, v123, v155
	global_store_dword v139, v155, s[84:85]
	v_add_f32_e32 v156, v124, v156
	global_store_dword v140, v156, s[84:85]
	v_add_f32_e32 v157, v125, v157
	global_store_dword v141, v157, s[84:85]
	v_add_f32_e32 v158, v126, v158
	global_store_dword v142, v158, s[84:85]
	v_add_f32_e32 v159, v127, v159
	global_store_dword v143, v159, s[84:85]
	v_add_u32_e32 v128, 0x20000, v202
	global_load_dword v144, v128, s[68:69]
	v_add_u32_e32 v129, 0x20000, v203
	global_load_dword v145, v129, s[68:69]
	v_add_u32_e32 v130, 0x20000, v204
	global_load_dword v146, v130, s[68:69]
	v_add_u32_e32 v131, 0x20000, v205
	global_load_dword v147, v131, s[68:69]
	v_add_u32_e32 v132, 0x20000, v206
	global_load_dword v148, v132, s[68:69]
	v_add_u32_e32 v133, 0x20000, v207
	global_load_dword v149, v133, s[68:69]
	v_add_u32_e32 v134, 0x20000, v208
	global_load_dword v150, v134, s[68:69]
	v_add_u32_e32 v135, 0x20000, v209
	global_load_dword v151, v135, s[68:69]
	v_add_u32_e32 v136, 0x20000, v210
	global_load_dword v152, v136, s[68:69]
	v_add_u32_e32 v137, 0x20000, v211
	global_load_dword v153, v137, s[68:69]
	v_add_u32_e32 v138, 0x20000, v212
	global_load_dword v154, v138, s[68:69]
	v_add_u32_e32 v139, 0x20000, v213
	global_load_dword v155, v139, s[68:69]
	v_add_u32_e32 v140, 0x20000, v214
	global_load_dword v156, v140, s[68:69]
	v_add_u32_e32 v141, 0x20000, v215
	global_load_dword v157, v141, s[68:69]
	v_add_u32_e32 v142, 0x20000, v216
	global_load_dword v158, v142, s[68:69]
	v_add_u32_e32 v143, 0x20000, v217
	global_load_dword v159, v143, s[68:69]
	s_waitcnt vmcnt(32)
	v_add_f32_e32 v236, v96, v236
	global_store_dword v160, v236, s[84:85]
	v_add_f32_e32 v237, v97, v237
	global_store_dword v161, v237, s[84:85]
	v_add_f32_e32 v238, v98, v238
	global_store_dword v162, v238, s[84:85]
	v_add_f32_e32 v239, v99, v239
	global_store_dword v163, v239, s[84:85]
	v_add_f32_e32 v240, v100, v240
	global_store_dword v164, v240, s[84:85]
	v_add_f32_e32 v241, v101, v241
	global_store_dword v165, v241, s[84:85]
	v_add_f32_e32 v242, v102, v242
	global_store_dword v166, v242, s[84:85]
	v_add_f32_e32 v243, v103, v243
	global_store_dword v167, v243, s[84:85]
	v_add_f32_e32 v244, v104, v244
	global_store_dword v168, v244, s[84:85]
	v_add_f32_e32 v245, v105, v245
	global_store_dword v169, v245, s[84:85]
	v_add_f32_e32 v246, v106, v246
	global_store_dword v170, v246, s[84:85]
	v_add_f32_e32 v247, v107, v247
	global_store_dword v171, v247, s[84:85]
	v_add_f32_e32 v248, v108, v248
	global_store_dword v172, v248, s[84:85]
	v_add_f32_e32 v249, v109, v249
	global_store_dword v173, v249, s[84:85]
	v_add_f32_e32 v250, v110, v250
	global_store_dword v174, v250, s[84:85]
	v_add_f32_e32 v251, v111, v251
	global_store_dword v175, v251, s[84:85]
	v_add_u32_e32 v160, 0x20080, v202
	global_load_dword v236, v160, s[68:69]
	v_add_u32_e32 v161, 0x20080, v203
	global_load_dword v237, v161, s[68:69]
	v_add_u32_e32 v162, 0x20080, v204
	global_load_dword v238, v162, s[68:69]
	v_add_u32_e32 v163, 0x20080, v205
	global_load_dword v239, v163, s[68:69]
	v_add_u32_e32 v164, 0x20080, v206
	global_load_dword v240, v164, s[68:69]
	v_add_u32_e32 v165, 0x20080, v207
	global_load_dword v241, v165, s[68:69]
	v_add_u32_e32 v166, 0x20080, v208
	global_load_dword v242, v166, s[68:69]
	v_add_u32_e32 v167, 0x20080, v209
	global_load_dword v243, v167, s[68:69]
	v_add_u32_e32 v168, 0x20080, v210
	global_load_dword v244, v168, s[68:69]
	v_add_u32_e32 v169, 0x20080, v211
	global_load_dword v245, v169, s[68:69]
	v_add_u32_e32 v170, 0x20080, v212
	global_load_dword v246, v170, s[68:69]
	v_add_u32_e32 v171, 0x20080, v213
	global_load_dword v247, v171, s[68:69]
	v_add_u32_e32 v172, 0x20080, v214
	global_load_dword v248, v172, s[68:69]
	v_add_u32_e32 v173, 0x20080, v215
	global_load_dword v249, v173, s[68:69]
	v_add_u32_e32 v174, 0x20080, v216
	global_load_dword v250, v174, s[68:69]
	v_add_u32_e32 v175, 0x20080, v217
	global_load_dword v251, v175, s[68:69]
	s_waitcnt vmcnt(32)
; DI int crow32(int r, int half) { return (r & 3) + 8 * (r >> 2) + 4 * half; }
; template <class Epi>
; DI void gemm256(const bf16_t* __restrict__ A, int lda, const bf16_t* __restrict__ B, int ldb, int K, int m0, int n0,
;                 bf16_t* sA, bf16_t* sB, Epi epi) {
;     ...
; #pragma unroll
;   for (int i = 0; i < 4; ++i)
; #pragma unroll
;     for (int j = 0; j < 2; ++j)
; #pragma unroll
;       for (int r = 0; r < 16; ++r) {
;         const int m = m0 + wm * 128 + i * 32 + crow32(r, lane >> 5);
;         const int n = n0 + wn * 64 + j * 32 + (lane & 31);
;         epi(m, n, acc[i][j][r]);
;       }
; __global__ void __launch_bounds__(256, 2) hymba_mega(Params p) {
;     ...
;       const int mt = (tile & 7) * 8 + (tile >> 6), nt = (tile >> 3) & 7;
;       gemm256((const bf16_t*)(ws + OFF_MX), 1024, (const bf16_t*)(ws + OFF_WOUTT), 1024, 1024, mt * 256, nt * 128, sA, (bf16_t*)(smem + 36864),
;               [&](int m, int n, float v) { out[(size_t)m * 1024 + n] = x[(size_t)m * 1024 + n] + v; });
	v_add_f32_e32 v144, v80, v144
	global_store_dword v128, v144, s[84:85]
	v_add_f32_e32 v145, v81, v145
	global_store_dword v129, v145, s[84:85]
	v_add_f32_e32 v146, v82, v146
	global_store_dword v130, v146, s[84:85]
	v_add_f32_e32 v147, v83, v147
	global_store_dword v131, v147, s[84:85]
	v_add_f32_e32 v148, v84, v148
	global_store_dword v132, v148, s[84:85]
	v_add_f32_e32 v149, v85, v149
	global_store_dword v133, v149, s[84:85]
	v_add_f32_e32 v150, v86, v150
	global_store_dword v134, v150, s[84:85]
	v_add_f32_e32 v151, v87, v151
	global_store_dword v135, v151, s[84:85]
	v_add_f32_e32 v152, v88, v152
	global_store_dword v136, v152, s[84:85]
	v_add_f32_e32 v153, v89, v153
	global_store_dword v137, v153, s[84:85]
	v_add_f32_e32 v154, v90, v154
	global_store_dword v138, v154, s[84:85]
	v_add_f32_e32 v155, v91, v155
	global_store_dword v139, v155, s[84:85]
	v_add_f32_e32 v156, v92, v156
	global_store_dword v140, v156, s[84:85]
	v_add_f32_e32 v157, v93, v157
	global_store_dword v141, v157, s[84:85]
	v_add_f32_e32 v158, v94, v158
	global_store_dword v142, v158, s[84:85]
	v_add_f32_e32 v159, v95, v159
	global_store_dword v143, v159, s[84:85]
	v_add_u32_e32 v128, 0x40000, v202
	global_load_dword v144, v128, s[68:69]
	v_add_u32_e32 v129, 0x40000, v203
	global_load_dword v145, v129, s[68:69]
	v_add_u32_e32 v130, 0x40000, v204
	global_load_dword v146, v130, s[68:69]
	v_add_u32_e32 v131, 0x40000, v205
	global_load_dword v147, v131, s[68:69]
	v_add_u32_e32 v132, 0x40000, v206
	global_load_dword v148, v132, s[68:69]
	v_add_u32_e32 v133, 0x40000, v207
	global_load_dword v149, v133, s[68:69]
	v_add_u32_e32 v134, 0x40000, v208
	global_load_dword v150, v134, s[68:69]
	v_add_u32_e32 v135, 0x40000, v209
	global_load_dword v151, v135, s[68:69]
	v_add_u32_e32 v136, 0x40000, v210
	global_load_dword v152, v136, s[68:69]
	v_add_u32_e32 v137, 0x40000, v211
	global_load_dword v153, v137, s[68:69]
	v_add_u32_e32 v138, 0x40000, v212
	global_load_dword v154, v138, s[68:69]
	v_add_u32_e32 v139, 0x40000, v213
	global_load_dword v155, v139, s[68:69]
	v_add_u32_e32 v140, 0x40000, v214
	global_load_dword v156, v140, s[68:69]
	v_add_u32_e32 v141, 0x40000, v215
	global_load_dword v157, v141, s[68:69]
	v_add_u32_e32 v142, 0x40000, v216
	global_load_dword v158, v142, s[68:69]
	v_add_u32_e32 v143, 0x40000, v217
	global_load_dword v159, v143, s[68:69]
	s_waitcnt vmcnt(32)
	v_add_f32_e32 v236, v64, v236
	global_store_dword v160, v236, s[84:85]
	v_add_f32_e32 v237, v65, v237
	global_store_dword v161, v237, s[84:85]
	v_add_f32_e32 v238, v66, v238
	global_store_dword v162, v238, s[84:85]
	v_add_f32_e32 v239, v67, v239
	global_store_dword v163, v239, s[84:85]
	v_add_f32_e32 v240, v68, v240
	global_store_dword v164, v240, s[84:85]
	v_add_f32_e32 v241, v69, v241
	global_store_dword v165, v241, s[84:85]
	v_add_f32_e32 v242, v70, v242
	global_store_dword v166, v242, s[84:85]
	v_add_f32_e32 v243, v71, v243
	global_store_dword v167, v243, s[84:85]
	v_add_f32_e32 v244, v72, v244
	global_store_dword v168, v244, s[84:85]
	v_add_f32_e32 v245, v73, v245
	global_store_dword v169, v245, s[84:85]
	v_add_f32_e32 v246, v74, v246
	global_store_dword v170, v246, s[84:85]
	v_add_f32_e32 v247, v75, v247
	global_store_dword v171, v247, s[84:85]
	v_add_f32_e32 v248, v76, v248
	global_store_dword v172, v248, s[84:85]
	v_add_f32_e32 v249, v77, v249
	global_store_dword v173, v249, s[84:85]
	v_add_f32_e32 v250, v78, v250
	global_store_dword v174, v250, s[84:85]
	v_add_f32_e32 v251, v79, v251
	global_store_dword v175, v251, s[84:85]
	v_add_u32_e32 v160, 0x40080, v202
	global_load_dword v236, v160, s[68:69]
	v_add_u32_e32 v161, 0x40080, v203
	global_load_dword v237, v161, s[68:69]
	v_add_u32_e32 v162, 0x40080, v204
	global_load_dword v238, v162, s[68:69]
	v_add_u32_e32 v163, 0x40080, v205
	global_load_dword v239, v163, s[68:69]
	v_add_u32_e32 v164, 0x40080, v206
	global_load_dword v240, v164, s[68:69]
	v_add_u32_e32 v165, 0x40080, v207
	global_load_dword v241, v165, s[68:69]
	v_add_u32_e32 v166, 0x40080, v208
	global_load_dword v242, v166, s[68:69]
	v_add_u32_e32 v167, 0x40080, v209
	global_load_dword v243, v167, s[68:69]
	v_add_u32_e32 v168, 0x40080, v210
	global_load_dword v244, v168, s[68:69]
	v_add_u32_e32 v169, 0x40080, v211
	global_load_dword v245, v169, s[68:69]
	v_add_u32_e32 v170, 0x40080, v212
	global_load_dword v246, v170, s[68:69]
	v_add_u32_e32 v171, 0x40080, v213
	global_load_dword v247, v171, s[68:69]
	v_add_u32_e32 v172, 0x40080, v214
	global_load_dword v248, v172, s[68:69]
	v_add_u32_e32 v173, 0x40080, v215
	global_load_dword v249, v173, s[68:69]
	v_add_u32_e32 v174, 0x40080, v216
	global_load_dword v250, v174, s[68:69]
	v_add_u32_e32 v175, 0x40080, v217
	global_load_dword v251, v175, s[68:69]
	s_waitcnt vmcnt(32)
; DI int crow32(int r, int half) { return (r & 3) + 8 * (r >> 2) + 4 * half; }
; template <class Epi>
; DI void gemm256(const bf16_t* __restrict__ A, int lda, const bf16_t* __restrict__ B, int ldb, int K, int m0, int n0,
;                 bf16_t* sA, bf16_t* sB, Epi epi) {
;     ...
; #pragma unroll
;   for (int i = 0; i < 4; ++i)
; #pragma unroll
;     for (int j = 0; j < 2; ++j)
; #pragma unroll
;       for (int r = 0; r < 16; ++r) {
;         const int m = m0 + wm * 128 + i * 32 + crow32(r, lane >> 5);
;         const int n = n0 + wn * 64 + j * 32 + (lane & 31);
;         epi(m, n, acc[i][j][r]);
;       }
; __global__ void __launch_bounds__(256, 2) hymba_mega(Params p) {
;     ...
;       const int mt = (tile & 7) * 8 + (tile >> 6), nt = (tile >> 3) & 7;
;       gemm256((const bf16_t*)(ws + OFF_MX), 1024, (const bf16_t*)(ws + OFF_WOUTT), 1024, 1024, mt * 256, nt * 128, sA, (bf16_t*)(smem + 36864),
;               [&](int m, int n, float v) { out[(size_t)m * 1024 + n] = x[(size_t)m * 1024 + n] + v; });
	v_add_f32_e32 v144, v48, v144
	global_store_dword v128, v144, s[84:85]
	v_add_f32_e32 v145, v49, v145
	global_store_dword v129, v145, s[84:85]
	v_add_f32_e32 v146, v50, v146
	global_store_dword v130, v146, s[84:85]
	v_add_f32_e32 v147, v51, v147
	global_store_dword v131, v147, s[84:85]
	v_add_f32_e32 v148, v52, v148
	global_store_dword v132, v148, s[84:85]
	v_add_f32_e32 v149, v53, v149
	global_store_dword v133, v149, s[84:85]
	v_add_f32_e32 v150, v54, v150
	global_store_dword v134, v150, s[84:85]
	v_add_f32_e32 v151, v55, v151
	global_store_dword v135, v151, s[84:85]
	v_add_f32_e32 v152, v56, v152
	global_store_dword v136, v152, s[84:85]
	v_add_f32_e32 v153, v57, v153
	global_store_dword v137, v153, s[84:85]
	v_add_f32_e32 v154, v58, v154
	global_store_dword v138, v154, s[84:85]
	v_add_f32_e32 v155, v59, v155
	global_store_dword v139, v155, s[84:85]
	v_add_f32_e32 v156, v60, v156
	global_store_dword v140, v156, s[84:85]
	v_add_f32_e32 v157, v61, v157
	global_store_dword v141, v157, s[84:85]
	v_add_f32_e32 v158, v62, v158
	global_store_dword v142, v158, s[84:85]
	v_add_f32_e32 v159, v63, v159
	global_store_dword v143, v159, s[84:85]
	v_add_u32_e32 v128, 0x60000, v202
	global_load_dword v144, v128, s[68:69]
	v_add_u32_e32 v129, 0x60000, v203
	global_load_dword v145, v129, s[68:69]
	v_add_u32_e32 v130, 0x60000, v204
	global_load_dword v146, v130, s[68:69]
	v_add_u32_e32 v131, 0x60000, v205
	global_load_dword v147, v131, s[68:69]
	v_add_u32_e32 v132, 0x60000, v206
	global_load_dword v148, v132, s[68:69]
	v_add_u32_e32 v133, 0x60000, v207
	global_load_dword v149, v133, s[68:69]
	v_add_u32_e32 v134, 0x60000, v208
	global_load_dword v150, v134, s[68:69]
	v_add_u32_e32 v135, 0x60000, v209
	global_load_dword v151, v135, s[68:69]
	v_add_u32_e32 v136, 0x60000, v210
	global_load_dword v152, v136, s[68:69]
	v_add_u32_e32 v137, 0x60000, v211
	global_load_dword v153, v137, s[68:69]
	v_add_u32_e32 v138, 0x60000, v212
	global_load_dword v154, v138, s[68:69]
	v_add_u32_e32 v139, 0x60000, v213
	global_load_dword v155, v139, s[68:69]
	v_add_u32_e32 v140, 0x60000, v214
	global_load_dword v156, v140, s[68:69]
	v_add_u32_e32 v141, 0x60000, v215
	global_load_dword v157, v141, s[68:69]
	v_add_u32_e32 v142, 0x60000, v216
	global_load_dword v158, v142, s[68:69]
	v_add_u32_e32 v143, 0x60000, v217
	global_load_dword v159, v143, s[68:69]
	s_waitcnt vmcnt(32)
	v_add_f32_e32 v236, v32, v236
	global_store_dword v160, v236, s[84:85]
	v_add_f32_e32 v237, v33, v237
	global_store_dword v161, v237, s[84:85]
	v_add_f32_e32 v238, v34, v238
	global_store_dword v162, v238, s[84:85]
	v_add_f32_e32 v239, v35, v239
	global_store_dword v163, v239, s[84:85]
	v_add_f32_e32 v240, v36, v240
	global_store_dword v164, v240, s[84:85]
	v_add_f32_e32 v241, v37, v241
	global_store_dword v165, v241, s[84:85]
	v_add_f32_e32 v242, v38, v242
	global_store_dword v166, v242, s[84:85]
	v_add_f32_e32 v243, v39, v243
	global_store_dword v167, v243, s[84:85]
	v_add_f32_e32 v244, v40, v244
	global_store_dword v168, v244, s[84:85]
	v_add_f32_e32 v245, v41, v245
	global_store_dword v169, v245, s[84:85]
	v_add_f32_e32 v246, v42, v246
	global_store_dword v170, v246, s[84:85]
	v_add_f32_e32 v247, v43, v247
	global_store_dword v171, v247, s[84:85]
	v_add_f32_e32 v248, v44, v248
	global_store_dword v172, v248, s[84:85]
	v_add_f32_e32 v249, v45, v249
	global_store_dword v173, v249, s[84:85]
	v_add_f32_e32 v250, v46, v250
	global_store_dword v174, v250, s[84:85]
	v_add_f32_e32 v251, v47, v251
	global_store_dword v175, v251, s[84:85]
	v_add_u32_e32 v160, 0x60080, v202
	global_load_dword v236, v160, s[68:69]
	v_add_u32_e32 v161, 0x60080, v203
	global_load_dword v237, v161, s[68:69]
	v_add_u32_e32 v162, 0x60080, v204
	global_load_dword v238, v162, s[68:69]
	v_add_u32_e32 v163, 0x60080, v205
	global_load_dword v239, v163, s[68:69]
	v_add_u32_e32 v164, 0x60080, v206
	global_load_dword v240, v164, s[68:69]
	v_add_u32_e32 v165, 0x60080, v207
	global_load_dword v241, v165, s[68:69]
	v_add_u32_e32 v166, 0x60080, v208
	global_load_dword v242, v166, s[68:69]
	v_add_u32_e32 v167, 0x60080, v209
	global_load_dword v243, v167, s[68:69]
	v_add_u32_e32 v168, 0x60080, v210
	global_load_dword v244, v168, s[68:69]
	v_add_u32_e32 v169, 0x60080, v211
	global_load_dword v245, v169, s[68:69]
	v_add_u32_e32 v170, 0x60080, v212
	global_load_dword v246, v170, s[68:69]
	v_add_u32_e32 v171, 0x60080, v213
	global_load_dword v247, v171, s[68:69]
	v_add_u32_e32 v172, 0x60080, v214
	global_load_dword v248, v172, s[68:69]
	v_add_u32_e32 v173, 0x60080, v215
	global_load_dword v249, v173, s[68:69]
	v_add_u32_e32 v174, 0x60080, v216
	global_load_dword v250, v174, s[68:69]
	v_add_u32_e32 v175, 0x60080, v217
	global_load_dword v251, v175, s[68:69]
	s_waitcnt vmcnt(32)
; DI int crow32(int r, int half) { return (r & 3) + 8 * (r >> 2) + 4 * half; }
; template <class Epi>
; DI void gemm256(const bf16_t* __restrict__ A, int lda, const bf16_t* __restrict__ B, int ldb, int K, int m0, int n0,
;                 bf16_t* sA, bf16_t* sB, Epi epi) {
;     ...
; #pragma unroll
;   for (int i = 0; i < 4; ++i)
; #pragma unroll
;     for (int j = 0; j < 2; ++j)
; #pragma unroll
;       for (int r = 0; r < 16; ++r) {
;         const int m = m0 + wm * 128 + i * 32 + crow32(r, lane >> 5);
;         const int n = n0 + wn * 64 + j * 32 + (lane & 31);
;         epi(m, n, acc[i][j][r]);
;       }
; __global__ void __launch_bounds__(256, 2) hymba_mega(Params p) {
;     ...
;     for (int tile = blockIdx.x; tile < 64 * 8; tile += gridDim.x) {
;       const int mt = (tile & 7) * 8 + (tile >> 6), nt = (tile >> 3) & 7;
;       gemm256((const bf16_t*)(ws + OFF_MX), 1024, (const bf16_t*)(ws + OFF_WOUTT), 1024, 1024, mt * 256, nt * 128, sA, (bf16_t*)(smem + 36864),
;               [&](int m, int n, float v) { out[(size_t)m * 1024 + n] = x[(size_t)m * 1024 + n] + v; });
;     }
	v_add_f32_e32 v144, v16, v144
	global_store_dword v128, v144, s[84:85]
	v_add_f32_e32 v145, v17, v145
	global_store_dword v129, v145, s[84:85]
	v_add_f32_e32 v146, v18, v146
	global_store_dword v130, v146, s[84:85]
	v_add_f32_e32 v147, v19, v147
	global_store_dword v131, v147, s[84:85]
	v_add_f32_e32 v148, v20, v148
	global_store_dword v132, v148, s[84:85]
	v_add_f32_e32 v149, v21, v149
	global_store_dword v133, v149, s[84:85]
	v_add_f32_e32 v150, v22, v150
	global_store_dword v134, v150, s[84:85]
	v_add_f32_e32 v151, v23, v151
	global_store_dword v135, v151, s[84:85]
	v_add_f32_e32 v152, v24, v152
	global_store_dword v136, v152, s[84:85]
	v_add_f32_e32 v153, v25, v153
	global_store_dword v137, v153, s[84:85]
	v_add_f32_e32 v154, v26, v154
	global_store_dword v138, v154, s[84:85]
	v_add_f32_e32 v155, v27, v155
	global_store_dword v139, v155, s[84:85]
	v_add_f32_e32 v156, v28, v156
	global_store_dword v140, v156, s[84:85]
	v_add_f32_e32 v157, v29, v157
	global_store_dword v141, v157, s[84:85]
	v_add_f32_e32 v158, v30, v158
	global_store_dword v142, v158, s[84:85]
	v_add_f32_e32 v159, v31, v159
	global_store_dword v143, v159, s[84:85]
	s_waitcnt vmcnt(16)
	v_add_f32_e32 v236, v0, v236
	global_store_dword v160, v236, s[84:85]
	v_add_f32_e32 v237, v1, v237
	global_store_dword v161, v237, s[84:85]
	v_add_f32_e32 v238, v2, v238
	global_store_dword v162, v238, s[84:85]
	v_add_f32_e32 v239, v3, v239
	global_store_dword v163, v239, s[84:85]
	v_add_f32_e32 v240, v4, v240
	global_store_dword v164, v240, s[84:85]
	v_add_f32_e32 v241, v5, v241
	global_store_dword v165, v241, s[84:85]
	v_add_f32_e32 v242, v6, v242
	global_store_dword v166, v242, s[84:85]
	v_add_f32_e32 v243, v7, v243
	global_store_dword v167, v243, s[84:85]
	v_add_f32_e32 v244, v8, v244
	global_store_dword v168, v244, s[84:85]
	v_add_f32_e32 v245, v9, v245
	global_store_dword v169, v245, s[84:85]
	v_add_f32_e32 v246, v10, v246
	global_store_dword v170, v246, s[84:85]
	v_add_f32_e32 v247, v11, v247
	global_store_dword v171, v247, s[84:85]
	v_add_f32_e32 v248, v12, v248
	global_store_dword v172, v248, s[84:85]
	v_add_f32_e32 v249, v13, v249
	global_store_dword v173, v249, s[84:85]
	v_add_f32_e32 v250, v14, v250
	global_store_dword v174, v250, s[84:85]
	v_add_f32_e32 v251, v15, v251
	global_store_dword v175, v251, s[84:85]
	s_add_i32 s43, s43, s88
	s_add_i32 s0, s0, s1
	s_add_i32 s3, s3, s4
	s_cmpk_gt_i32 s43, 0x1ff
	s_cbranch_scc0 .LBB0_920

; __global__ void __launch_bounds__(256, 2) hymba_mega(Params p) {
;   cg::grid_group grid = cg::this_grid();
;   __shared__ __attribute__((aligned(16))) char smem[SMEM_BYTES];
	.amdhsa_kernel _Z10hymba_mega6Params
		.amdhsa_group_segment_fixed_size 77840
		.amdhsa_private_segment_fixed_size 0
		.amdhsa_kernarg_size 464
		.amdhsa_user_sgpr_count 2
		.amdhsa_user_sgpr_dispatch_ptr 0
		.amdhsa_user_sgpr_queue_ptr 0
		.amdhsa_user_sgpr_kernarg_segment_ptr 1
		.amdhsa_user_sgpr_dispatch_id 0
		.amdhsa_user_sgpr_kernarg_preload_length 0
		.amdhsa_user_sgpr_kernarg_preload_offset 0
		.amdhsa_user_sgpr_private_segment_size 0
		.amdhsa_uses_dynamic_stack 0
		.amdhsa_enable_private_segment 0
		.amdhsa_system_sgpr_workgroup_id_x 1
		.amdhsa_system_sgpr_workgroup_id_y 0
		.amdhsa_system_sgpr_workgroup_id_z 0
		.amdhsa_system_sgpr_workgroup_info 0
		.amdhsa_system_vgpr_workitem_id 2
		.amdhsa_next_free_vgpr 252
		.amdhsa_next_free_sgpr 102
		.amdhsa_accum_offset 252
		.amdhsa_reserve_vcc 1
		.amdhsa_float_round_mode_32 0
		.amdhsa_float_round_mode_16_64 0
		.amdhsa_float_denorm_mode_32 3
		.amdhsa_float_denorm_mode_16_64 3
		.amdhsa_dx10_clamp 1
		.amdhsa_ieee_mode 1
		.amdhsa_fp16_overflow 0
		.amdhsa_tg_split 0
		.amdhsa_exception_fp_ieee_invalid_op 0
		.amdhsa_exception_fp_denorm_src 0
		.amdhsa_exception_fp_ieee_div_zero 0
		.amdhsa_exception_fp_ieee_overflow 0
		.amdhsa_exception_fp_ieee_underflow 0
		.amdhsa_exception_fp_ieee_inexact 0
		.amdhsa_exception_int_div_zero 0
	.end_amdhsa_kernel

; __global__ void __launch_bounds__(256, 2) hymba_mega(Params p) {
;   cg::grid_group grid = cg::this_grid();
;   __shared__ __attribute__((aligned(16))) char smem[SMEM_BYTES];
amdhsa.kernels:
  - .agpr_count:     0
    .args:
      - .offset:         0
        .size:           208
        .value_kind:     by_value
      - .offset:         208
        .size:           4
        .value_kind:     hidden_block_count_x
      - .offset:         212
        .size:           4
        .value_kind:     hidden_block_count_y
      - .offset:         216
        .size:           4
        .value_kind:     hidden_block_count_z
      - .offset:         220
        .size:           2
        .value_kind:     hidden_group_size_x
      - .offset:         222
        .size:           2
        .value_kind:     hidden_group_size_y
      - .offset:         224
        .size:           2
        .value_kind:     hidden_group_size_z
      - .offset:         226
        .size:           2
        .value_kind:     hidden_remainder_x
      - .offset:         228
        .size:           2
        .value_kind:     hidden_remainder_y
      - .offset:         230
        .size:           2
        .value_kind:     hidden_remainder_z
      - .offset:         248
        .size:           8
        .value_kind:     hidden_global_offset_x
      - .offset:         256
        .size:           8
        .value_kind:     hidden_global_offset_y
      - .offset:         264
        .size:           8
        .value_kind:     hidden_global_offset_z
      - .offset:         272
        .size:           2
        .value_kind:     hidden_grid_dims
      - .offset:         296
        .size:           8
        .value_kind:     hidden_multigrid_sync_arg
    .group_segment_fixed_size: 77840
    .kernarg_segment_align: 8
    .kernarg_segment_size: 464
    .language:       OpenCL C
    .language_version:
      - 2
      - 0
    .max_flat_workgroup_size: 256
    .name:           _Z10hymba_mega6Params
    .private_segment_fixed_size: 0
    .sgpr_count:     108
    .sgpr_spill_count: 18
    .symbol:         _Z10hymba_mega6Params.kd
    .uniform_work_group_size: 1
    .uses_dynamic_stack: false
    .vgpr_count:     252
    .vgpr_spill_count: 0
    .wavefront_size: 64
